# fused phase gate units: dedicated straight-line sigmoid epilogue instead of the generic per-chunk mode dispatch (on top of the peeled first K-loop body)
# speedup vs baseline: 1.0132x; 1.0037x over previous
; __device__ __forceinline__ unsigned cvtpk(float lo, float hi) { f32x2 v = {lo, hi}; bf16x2_t b = __builtin_convertvector(v, bf16x2_t); return __builtin_bit_cast(unsigned, b); }
; __device__ __forceinline__ float bflo(unsigned u) { return __uint_as_float(u << 16); }
; __device__ __forceinline__ float bfhi(unsigned u) { return __uint_as_float(u & 0xffff0000u); }
; __device__ __forceinline__ float sigmoidf_(float x) { return fast_rcp(1.f + __expf(-x)); }
;     __device__ __forceinline__ void operator()(const f32x4 (&acc)[2][2][4][2], const Unit& u, int wr, int wc, int fr, int fq) const {
;         const int mode = u.em;
;     ...
;                         if (mode == 1 || mode == 5) {
; #pragma unroll
;                             for (int e = 0; e < 4; ++e) { v0[e] = sigmoidf_(v0[e]); v1[e] = sigmoidf_(v1[e]); } }
;                         if (mode == 6) {
;                             const u32x4 gq = *(const u32x4*)(sG + rl * 256 + cl);
;                             v0[0] *= bflo(gq.x); v0[1] *= bfhi(gq.x); v0[2] *= bflo(gq.y); v0[3] *= bfhi(gq.y); v1[0] *= bflo(gq.z); v1[1] *= bfhi(gq.z); v1[2] *= bflo(gq.w); v1[3] *= bfhi(gq.w);
;                             if (u.br > 0) { const u32x4 mo = *(const u32x4*)(sM + rl * 256 + cl);
;                                 v0[0] += bflo(mo.x); v0[1] += bfhi(mo.x); v0[2] += bflo(mo.y); v0[3] += bfhi(mo.y); v1[0] += bflo(mo.z); v1[1] += bfhi(mo.z); v1[2] += bflo(mo.w); v1[3] += bfhi(mo.w); } }
;                         u32x4 w; w.x = cvtpk(v0[0], v0[1]); w.y = cvtpk(v0[2], v0[3]); w.z = cvtpk(v1[0], v1[1]); w.w = cvtpk(v1[2], v1[3]);
;                         if (mode == 5) *(u32x4*)(sG + rl * 256 + cl) = w;
;                         else if (mode == 6 && u.br < 2) *(u32x4*)(sM + rl * 256 + cl) = w;
.LBB0_423:
	s_cmp_eq_u32 s71, 6
	s_cbranch_scc1 .Lepi6
	s_cmp_eq_u32 s71, 5
	s_cbranch_scc1 .Lepi5
	s_cmp_lt_i32 s71, 5
	s_cbranch_scc1 .LBB0_426
	s_cmp_eq_u32 s71, 5
	s_cselect_b64 s[26:27], -1, 0
	s_cbranch_execz .LBB0_427
	s_branch .LBB0_428

; __device__ __forceinline__ unsigned cvtpk(float lo, float hi) { f32x2 v = {lo, hi}; bf16x2_t b = __builtin_convertvector(v, bf16x2_t); return __builtin_bit_cast(unsigned, b); }
; __device__ __forceinline__ float bflo(unsigned u) { return __uint_as_float(u << 16); }
; __device__ __forceinline__ float bfhi(unsigned u) { return __uint_as_float(u & 0xffff0000u); }
;     __device__ __forceinline__ void operator()(const f32x4 (&acc)[2][2][4][2], const Unit& u, int wr, int wc, int fr, int fq) const {
;     ...
;         for (int ai = 0; ai < 2; ++ai)
; #pragma unroll
;             for (int m = 0; m < 4; ++m) { const int rl = rl0 + ai * HALF + m * 16; const size_t row = (size_t)(u.pm * BM + rl); bf16_t* rowp = O + row * ldc;
; #pragma unroll
;                 for (int bj = 0; bj < 2; ++bj) { const int cl = cl0 + bj * HALF; const int col0 = u.pn * BM + cl; f32x4 v0 = acc[ai][bj][m][0], v1 = acc[ai][bj][m][1];
;                     if (mode == 2) {
;                         float r[4];
; #pragma unroll
;                         for (int e = 0; e < 4; ++e) r[e] = v0[e] * sigmoidf_(v0[e]) * v1[e];
;                         u32x2 w; w.x = cvtpk(r[0], r[1]); w.y = cvtpk(r[2], r[3]);
;                         *(u32x2*)(rowp + (col0 >> 1)) = w;
;                     } else {
;                         if (mode == 1 || mode == 5) {
; #pragma unroll
;                             for (int e = 0; e < 4; ++e) { v0[e] = sigmoidf_(v0[e]); v1[e] = sigmoidf_(v1[e]); } }
;                         if (mode == 6) {
;                             const u32x4 gq = *(const u32x4*)(sG + rl * 256 + cl);
;                             v0[0] *= bflo(gq.x); v0[1] *= bfhi(gq.x); v0[2] *= bflo(gq.y); v0[3] *= bfhi(gq.y); v1[0] *= bflo(gq.z); v1[1] *= bfhi(gq.z); v1[2] *= bflo(gq.w); v1[3] *= bfhi(gq.w);
;                             if (u.br > 0) { const u32x4 mo = *(const u32x4*)(sM + rl * 256 + cl);
;                                 v0[0] += bflo(mo.x); v0[1] += bfhi(mo.x); v0[2] += bflo(mo.y); v0[3] += bfhi(mo.y); v1[0] += bflo(mo.z); v1[1] += bfhi(mo.z); v1[2] += bflo(mo.w); v1[3] += bfhi(mo.w); } }
;                         u32x4 w; w.x = cvtpk(v0[0], v0[1]); w.y = cvtpk(v0[2], v0[3]); w.z = cvtpk(v1[0], v1[1]); w.w = cvtpk(v1[2], v1[3]);
;                         if (mode == 5) *(u32x4*)(sG + rl * 256 + cl) = w;
.Lepi5:
	v_lshlrev_b32_e32 v228, 9, v184
	v_lshl_add_u32 v228, v150, 1, v228
	v_readlane_b32 s74, v252, 54
	v_readlane_b32 s75, v252, 55
	s_nop 3
	s_mov_b32 s90, s74
	s_mov_b32 s91, s75
	v_mul_f32_e32 v136, 0xbfb8aa3b, v132
	v_mul_f32_e32 v137, 0xbfb8aa3b, v133
	v_mul_f32_e32 v138, 0xbfb8aa3b, v134
	v_mul_f32_e32 v139, 0xbfb8aa3b, v135
	v_mul_f32_e32 v140, 0xbfb8aa3b, v128
	v_mul_f32_e32 v141, 0xbfb8aa3b, v129
	v_mul_f32_e32 v142, 0xbfb8aa3b, v130
	v_mul_f32_e32 v143, 0xbfb8aa3b, v131
	v_exp_f32_e32 v136, v136
	v_exp_f32_e32 v137, v137
	v_exp_f32_e32 v138, v138
	v_exp_f32_e32 v139, v139
	v_exp_f32_e32 v140, v140
	v_exp_f32_e32 v141, v141
	v_exp_f32_e32 v142, v142
	v_exp_f32_e32 v143, v143
	v_add_f32_e32 v136, 1.0, v136
	v_add_f32_e32 v137, 1.0, v137
	v_add_f32_e32 v138, 1.0, v138
	v_add_f32_e32 v139, 1.0, v139
	v_add_f32_e32 v140, 1.0, v140
	v_add_f32_e32 v141, 1.0, v141
	v_add_f32_e32 v142, 1.0, v142
	v_add_f32_e32 v143, 1.0, v143
	v_rcp_f32_e32 v136, v136
	v_rcp_f32_e32 v137, v137
	v_rcp_f32_e32 v138, v138
	v_rcp_f32_e32 v139, v139
	v_rcp_f32_e32 v140, v140
	v_rcp_f32_e32 v141, v141
	v_rcp_f32_e32 v142, v142
	v_rcp_f32_e32 v143, v143
	v_cvt_pk_bf16_f32 v246, v136, v137
	v_cvt_pk_bf16_f32 v247, v138, v139
	v_cvt_pk_bf16_f32 v248, v140, v141
	v_cvt_pk_bf16_f32 v249, v142, v143
	global_store_dwordx4 v228, v[246:249], s[90:91]
	v_mul_f32_e32 v136, 0xbfb8aa3b, v100
	v_mul_f32_e32 v137, 0xbfb8aa3b, v101
	v_mul_f32_e32 v138, 0xbfb8aa3b, v102
	v_mul_f32_e32 v139, 0xbfb8aa3b, v103
	v_mul_f32_e32 v140, 0xbfb8aa3b, v96
	v_mul_f32_e32 v141, 0xbfb8aa3b, v97
	v_mul_f32_e32 v142, 0xbfb8aa3b, v98
	v_mul_f32_e32 v143, 0xbfb8aa3b, v99
	v_exp_f32_e32 v136, v136
	v_exp_f32_e32 v137, v137
	v_exp_f32_e32 v138, v138
	v_exp_f32_e32 v139, v139
	v_exp_f32_e32 v140, v140
	v_exp_f32_e32 v141, v141
	v_exp_f32_e32 v142, v142
	v_exp_f32_e32 v143, v143
	v_add_f32_e32 v136, 1.0, v136
	v_add_f32_e32 v137, 1.0, v137
	v_add_f32_e32 v138, 1.0, v138
	v_add_f32_e32 v139, 1.0, v139
	v_add_f32_e32 v140, 1.0, v140
	v_add_f32_e32 v141, 1.0, v141
	v_add_f32_e32 v142, 1.0, v142
	v_add_f32_e32 v143, 1.0, v143
	v_rcp_f32_e32 v136, v136
	v_rcp_f32_e32 v137, v137
	v_rcp_f32_e32 v138, v138
	v_rcp_f32_e32 v139, v139
	v_rcp_f32_e32 v140, v140
	v_rcp_f32_e32 v141, v141
	v_rcp_f32_e32 v142, v142
	v_rcp_f32_e32 v143, v143
	v_cvt_pk_bf16_f32 v210, v136, v137
	v_cvt_pk_bf16_f32 v211, v138, v139
	v_cvt_pk_bf16_f32 v212, v140, v141
	v_cvt_pk_bf16_f32 v213, v142, v143
	global_store_dwordx4 v228, v[210:213], s[90:91] offset:256
	s_add_u32 s90, s90, 0x2000
	s_addc_u32 s91, s91, 0
	v_mul_f32_e32 v136, 0xbfb8aa3b, v124
	v_mul_f32_e32 v137, 0xbfb8aa3b, v125
	v_mul_f32_e32 v138, 0xbfb8aa3b, v126
	v_mul_f32_e32 v139, 0xbfb8aa3b, v127
	v_mul_f32_e32 v140, 0xbfb8aa3b, v120
	v_mul_f32_e32 v141, 0xbfb8aa3b, v121
	v_mul_f32_e32 v142, 0xbfb8aa3b, v122
	v_mul_f32_e32 v143, 0xbfb8aa3b, v123
	v_exp_f32_e32 v136, v136
	v_exp_f32_e32 v137, v137
	v_exp_f32_e32 v138, v138
	v_exp_f32_e32 v139, v139
	v_exp_f32_e32 v140, v140
	v_exp_f32_e32 v141, v141
	v_exp_f32_e32 v142, v142
	v_exp_f32_e32 v143, v143
	v_add_f32_e32 v136, 1.0, v136
	v_add_f32_e32 v137, 1.0, v137
	v_add_f32_e32 v138, 1.0, v138
	v_add_f32_e32 v139, 1.0, v139
	v_add_f32_e32 v140, 1.0, v140
	v_add_f32_e32 v141, 1.0, v141
	v_add_f32_e32 v142, 1.0, v142
	v_add_f32_e32 v143, 1.0, v143
	v_rcp_f32_e32 v136, v136
	v_rcp_f32_e32 v137, v137
	v_rcp_f32_e32 v138, v138
	v_rcp_f32_e32 v139, v139
	v_rcp_f32_e32 v140, v140
	v_rcp_f32_e32 v141, v141
	v_rcp_f32_e32 v142, v142
	v_rcp_f32_e32 v143, v143
	v_cvt_pk_bf16_f32 v246, v136, v137
	v_cvt_pk_bf16_f32 v247, v138, v139
	v_cvt_pk_bf16_f32 v248, v140, v141
	v_cvt_pk_bf16_f32 v249, v142, v143
	global_store_dwordx4 v228, v[246:249], s[90:91]
	v_mul_f32_e32 v136, 0xbfb8aa3b, v92
	v_mul_f32_e32 v137, 0xbfb8aa3b, v93
	v_mul_f32_e32 v138, 0xbfb8aa3b, v94
	v_mul_f32_e32 v139, 0xbfb8aa3b, v95
	v_mul_f32_e32 v140, 0xbfb8aa3b, v88
	v_mul_f32_e32 v141, 0xbfb8aa3b, v89
	v_mul_f32_e32 v142, 0xbfb8aa3b, v90
	v_mul_f32_e32 v143, 0xbfb8aa3b, v91
	v_exp_f32_e32 v136, v136
	v_exp_f32_e32 v137, v137
	v_exp_f32_e32 v138, v138
	v_exp_f32_e32 v139, v139
	v_exp_f32_e32 v140, v140
	v_exp_f32_e32 v141, v141
	v_exp_f32_e32 v142, v142
	v_exp_f32_e32 v143, v143
	v_add_f32_e32 v136, 1.0, v136
	v_add_f32_e32 v137, 1.0, v137
	v_add_f32_e32 v138, 1.0, v138
	v_add_f32_e32 v139, 1.0, v139
	v_add_f32_e32 v140, 1.0, v140
	v_add_f32_e32 v141, 1.0, v141
	v_add_f32_e32 v142, 1.0, v142
	v_add_f32_e32 v143, 1.0, v143
	v_rcp_f32_e32 v136, v136
	v_rcp_f32_e32 v137, v137
	v_rcp_f32_e32 v138, v138
	v_rcp_f32_e32 v139, v139
	v_rcp_f32_e32 v140, v140
	v_rcp_f32_e32 v141, v141
	v_rcp_f32_e32 v142, v142
	v_rcp_f32_e32 v143, v143
	v_cvt_pk_bf16_f32 v210, v136, v137
	v_cvt_pk_bf16_f32 v211, v138, v139
	v_cvt_pk_bf16_f32 v212, v140, v141
	v_cvt_pk_bf16_f32 v213, v142, v143
	global_store_dwordx4 v228, v[210:213], s[90:91] offset:256
	s_add_u32 s90, s90, 0x2000
	s_addc_u32 s91, s91, 0
	v_mul_f32_e32 v136, 0xbfb8aa3b, v116
	v_mul_f32_e32 v137, 0xbfb8aa3b, v117
	v_mul_f32_e32 v138, 0xbfb8aa3b, v118
	v_mul_f32_e32 v139, 0xbfb8aa3b, v119
	v_mul_f32_e32 v140, 0xbfb8aa3b, v112
	v_mul_f32_e32 v141, 0xbfb8aa3b, v113
	v_mul_f32_e32 v142, 0xbfb8aa3b, v114
	v_mul_f32_e32 v143, 0xbfb8aa3b, v115
	v_exp_f32_e32 v136, v136
	v_exp_f32_e32 v137, v137
	v_exp_f32_e32 v138, v138
	v_exp_f32_e32 v139, v139
	v_exp_f32_e32 v140, v140
	v_exp_f32_e32 v141, v141
	v_exp_f32_e32 v142, v142
	v_exp_f32_e32 v143, v143
	v_add_f32_e32 v136, 1.0, v136
	v_add_f32_e32 v137, 1.0, v137
	v_add_f32_e32 v138, 1.0, v138
	v_add_f32_e32 v139, 1.0, v139
	v_add_f32_e32 v140, 1.0, v140
	v_add_f32_e32 v141, 1.0, v141
; __device__ __forceinline__ unsigned cvtpk(float lo, float hi) { f32x2 v = {lo, hi}; bf16x2_t b = __builtin_convertvector(v, bf16x2_t); return __builtin_bit_cast(unsigned, b); }
; __device__ __forceinline__ float bflo(unsigned u) { return __uint_as_float(u << 16); }
; __device__ __forceinline__ float bfhi(unsigned u) { return __uint_as_float(u & 0xffff0000u); }
; __device__ __forceinline__ float sigmoidf_(float x) { return fast_rcp(1.f + __expf(-x)); }
;     __device__ __forceinline__ void operator()(const f32x4 (&acc)[2][2][4][2], const Unit& u, int wr, int wc, int fr, int fq) const {
;     ...
;                         if (mode == 1 || mode == 5) {
; #pragma unroll
;                             for (int e = 0; e < 4; ++e) { v0[e] = sigmoidf_(v0[e]); v1[e] = sigmoidf_(v1[e]); } }
;                         if (mode == 6) {
;                             const u32x4 gq = *(const u32x4*)(sG + rl * 256 + cl);
;                             v0[0] *= bflo(gq.x); v0[1] *= bfhi(gq.x); v0[2] *= bflo(gq.y); v0[3] *= bfhi(gq.y); v1[0] *= bflo(gq.z); v1[1] *= bfhi(gq.z); v1[2] *= bflo(gq.w); v1[3] *= bfhi(gq.w);
;                             if (u.br > 0) { const u32x4 mo = *(const u32x4*)(sM + rl * 256 + cl);
;                                 v0[0] += bflo(mo.x); v0[1] += bfhi(mo.x); v0[2] += bflo(mo.y); v0[3] += bfhi(mo.y); v1[0] += bflo(mo.z); v1[1] += bfhi(mo.z); v1[2] += bflo(mo.w); v1[3] += bfhi(mo.w); } }
;                         u32x4 w; w.x = cvtpk(v0[0], v0[1]); w.y = cvtpk(v0[2], v0[3]); w.z = cvtpk(v1[0], v1[1]); w.w = cvtpk(v1[2], v1[3]);
;                         if (mode == 5) *(u32x4*)(sG + rl * 256 + cl) = w;
	v_add_f32_e32 v142, 1.0, v142
	v_add_f32_e32 v143, 1.0, v143
	v_rcp_f32_e32 v136, v136
	v_rcp_f32_e32 v137, v137
	v_rcp_f32_e32 v138, v138
	v_rcp_f32_e32 v139, v139
	v_rcp_f32_e32 v140, v140
	v_rcp_f32_e32 v141, v141
	v_rcp_f32_e32 v142, v142
	v_rcp_f32_e32 v143, v143
	v_cvt_pk_bf16_f32 v246, v136, v137
	v_cvt_pk_bf16_f32 v247, v138, v139
	v_cvt_pk_bf16_f32 v248, v140, v141
	v_cvt_pk_bf16_f32 v249, v142, v143
	global_store_dwordx4 v228, v[246:249], s[90:91]
	v_mul_f32_e32 v136, 0xbfb8aa3b, v84
	v_mul_f32_e32 v137, 0xbfb8aa3b, v85
	v_mul_f32_e32 v138, 0xbfb8aa3b, v86
	v_mul_f32_e32 v139, 0xbfb8aa3b, v87
	v_mul_f32_e32 v140, 0xbfb8aa3b, v80
	v_mul_f32_e32 v141, 0xbfb8aa3b, v81
	v_mul_f32_e32 v142, 0xbfb8aa3b, v82
	v_mul_f32_e32 v143, 0xbfb8aa3b, v83
	v_exp_f32_e32 v136, v136
	v_exp_f32_e32 v137, v137
	v_exp_f32_e32 v138, v138
	v_exp_f32_e32 v139, v139
	v_exp_f32_e32 v140, v140
	v_exp_f32_e32 v141, v141
	v_exp_f32_e32 v142, v142
	v_exp_f32_e32 v143, v143
	v_add_f32_e32 v136, 1.0, v136
	v_add_f32_e32 v137, 1.0, v137
	v_add_f32_e32 v138, 1.0, v138
	v_add_f32_e32 v139, 1.0, v139
	v_add_f32_e32 v140, 1.0, v140
	v_add_f32_e32 v141, 1.0, v141
	v_add_f32_e32 v142, 1.0, v142
	v_add_f32_e32 v143, 1.0, v143
	v_rcp_f32_e32 v136, v136
	v_rcp_f32_e32 v137, v137
	v_rcp_f32_e32 v138, v138
	v_rcp_f32_e32 v139, v139
	v_rcp_f32_e32 v140, v140
	v_rcp_f32_e32 v141, v141
	v_rcp_f32_e32 v142, v142
	v_rcp_f32_e32 v143, v143
	v_cvt_pk_bf16_f32 v210, v136, v137
	v_cvt_pk_bf16_f32 v211, v138, v139
	v_cvt_pk_bf16_f32 v212, v140, v141
	v_cvt_pk_bf16_f32 v213, v142, v143
	global_store_dwordx4 v228, v[210:213], s[90:91] offset:256
	s_add_u32 s90, s90, 0x2000
	s_addc_u32 s91, s91, 0
	v_mul_f32_e32 v136, 0xbfb8aa3b, v108
	v_mul_f32_e32 v137, 0xbfb8aa3b, v109
	v_mul_f32_e32 v138, 0xbfb8aa3b, v110
	v_mul_f32_e32 v139, 0xbfb8aa3b, v111
	v_mul_f32_e32 v140, 0xbfb8aa3b, v104
	v_mul_f32_e32 v141, 0xbfb8aa3b, v105
	v_mul_f32_e32 v142, 0xbfb8aa3b, v106
	v_mul_f32_e32 v143, 0xbfb8aa3b, v107
	v_exp_f32_e32 v136, v136
	v_exp_f32_e32 v137, v137
	v_exp_f32_e32 v138, v138
	v_exp_f32_e32 v139, v139
	v_exp_f32_e32 v140, v140
	v_exp_f32_e32 v141, v141
	v_exp_f32_e32 v142, v142
	v_exp_f32_e32 v143, v143
	v_add_f32_e32 v136, 1.0, v136
	v_add_f32_e32 v137, 1.0, v137
	v_add_f32_e32 v138, 1.0, v138
	v_add_f32_e32 v139, 1.0, v139
	v_add_f32_e32 v140, 1.0, v140
	v_add_f32_e32 v141, 1.0, v141
	v_add_f32_e32 v142, 1.0, v142
	v_add_f32_e32 v143, 1.0, v143
	v_rcp_f32_e32 v136, v136
	v_rcp_f32_e32 v137, v137
	v_rcp_f32_e32 v138, v138
	v_rcp_f32_e32 v139, v139
	v_rcp_f32_e32 v140, v140
	v_rcp_f32_e32 v141, v141
	v_rcp_f32_e32 v142, v142
	v_rcp_f32_e32 v143, v143
	v_cvt_pk_bf16_f32 v246, v136, v137
	v_cvt_pk_bf16_f32 v247, v138, v139
	v_cvt_pk_bf16_f32 v248, v140, v141
	v_cvt_pk_bf16_f32 v249, v142, v143
	global_store_dwordx4 v228, v[246:249], s[90:91]
	v_mul_f32_e32 v136, 0xbfb8aa3b, v76
	v_mul_f32_e32 v137, 0xbfb8aa3b, v77
	v_mul_f32_e32 v138, 0xbfb8aa3b, v78
	v_mul_f32_e32 v139, 0xbfb8aa3b, v79
	v_mul_f32_e32 v140, 0xbfb8aa3b, v72
	v_mul_f32_e32 v141, 0xbfb8aa3b, v73
	v_mul_f32_e32 v142, 0xbfb8aa3b, v74
	v_mul_f32_e32 v143, 0xbfb8aa3b, v75
	v_exp_f32_e32 v136, v136
	v_exp_f32_e32 v137, v137
	v_exp_f32_e32 v138, v138
	v_exp_f32_e32 v139, v139
	v_exp_f32_e32 v140, v140
	v_exp_f32_e32 v141, v141
	v_exp_f32_e32 v142, v142
	v_exp_f32_e32 v143, v143
	v_add_f32_e32 v136, 1.0, v136
	v_add_f32_e32 v137, 1.0, v137
	v_add_f32_e32 v138, 1.0, v138
	v_add_f32_e32 v139, 1.0, v139
	v_add_f32_e32 v140, 1.0, v140
	v_add_f32_e32 v141, 1.0, v141
	v_add_f32_e32 v142, 1.0, v142
	v_add_f32_e32 v143, 1.0, v143
	v_rcp_f32_e32 v136, v136
	v_rcp_f32_e32 v137, v137
	v_rcp_f32_e32 v138, v138
	v_rcp_f32_e32 v139, v139
	v_rcp_f32_e32 v140, v140
	v_rcp_f32_e32 v141, v141
	v_rcp_f32_e32 v142, v142
	v_rcp_f32_e32 v143, v143
	v_cvt_pk_bf16_f32 v210, v136, v137
	v_cvt_pk_bf16_f32 v211, v138, v139
	v_cvt_pk_bf16_f32 v212, v140, v141
	v_cvt_pk_bf16_f32 v213, v142, v143
	global_store_dwordx4 v228, v[210:213], s[90:91] offset:256
	s_add_u32 s90, s74, 0x10000
	s_addc_u32 s91, s75, 0
	v_mul_f32_e32 v136, 0xbfb8aa3b, v68
	v_mul_f32_e32 v137, 0xbfb8aa3b, v69
	v_mul_f32_e32 v138, 0xbfb8aa3b, v70
	v_mul_f32_e32 v139, 0xbfb8aa3b, v71
	v_mul_f32_e32 v140, 0xbfb8aa3b, v64
	v_mul_f32_e32 v141, 0xbfb8aa3b, v65
	v_mul_f32_e32 v142, 0xbfb8aa3b, v66
	v_mul_f32_e32 v143, 0xbfb8aa3b, v67
	v_exp_f32_e32 v136, v136
	v_exp_f32_e32 v137, v137
	v_exp_f32_e32 v138, v138
	v_exp_f32_e32 v139, v139
	v_exp_f32_e32 v140, v140
	v_exp_f32_e32 v141, v141
	v_exp_f32_e32 v142, v142
	v_exp_f32_e32 v143, v143
	v_add_f32_e32 v136, 1.0, v136
	v_add_f32_e32 v137, 1.0, v137
	v_add_f32_e32 v138, 1.0, v138
	v_add_f32_e32 v139, 1.0, v139
	v_add_f32_e32 v140, 1.0, v140
	v_add_f32_e32 v141, 1.0, v141
	v_add_f32_e32 v142, 1.0, v142
	v_add_f32_e32 v143, 1.0, v143
	v_rcp_f32_e32 v136, v136
	v_rcp_f32_e32 v137, v137
	v_rcp_f32_e32 v138, v138
	v_rcp_f32_e32 v139, v139
	v_rcp_f32_e32 v140, v140
	v_rcp_f32_e32 v141, v141
	v_rcp_f32_e32 v142, v142
	v_rcp_f32_e32 v143, v143
	v_cvt_pk_bf16_f32 v246, v136, v137
	v_cvt_pk_bf16_f32 v247, v138, v139
	v_cvt_pk_bf16_f32 v248, v140, v141
	v_cvt_pk_bf16_f32 v249, v142, v143
	global_store_dwordx4 v228, v[246:249], s[90:91]
	v_mul_f32_e32 v136, 0xbfb8aa3b, v36
	v_mul_f32_e32 v137, 0xbfb8aa3b, v37
	v_mul_f32_e32 v138, 0xbfb8aa3b, v38
	v_mul_f32_e32 v139, 0xbfb8aa3b, v39
	v_mul_f32_e32 v140, 0xbfb8aa3b, v32
	v_mul_f32_e32 v141, 0xbfb8aa3b, v33
	v_mul_f32_e32 v142, 0xbfb8aa3b, v34
	v_mul_f32_e32 v143, 0xbfb8aa3b, v35
	v_exp_f32_e32 v136, v136
	v_exp_f32_e32 v137, v137
	v_exp_f32_e32 v138, v138
	v_exp_f32_e32 v139, v139
	v_exp_f32_e32 v140, v140
; __device__ __forceinline__ unsigned cvtpk(float lo, float hi) { f32x2 v = {lo, hi}; bf16x2_t b = __builtin_convertvector(v, bf16x2_t); return __builtin_bit_cast(unsigned, b); }
; __device__ __forceinline__ float bflo(unsigned u) { return __uint_as_float(u << 16); }
; __device__ __forceinline__ float bfhi(unsigned u) { return __uint_as_float(u & 0xffff0000u); }
; __device__ __forceinline__ float sigmoidf_(float x) { return fast_rcp(1.f + __expf(-x)); }
;     __device__ __forceinline__ void operator()(const f32x4 (&acc)[2][2][4][2], const Unit& u, int wr, int wc, int fr, int fq) const {
;     ...
;                         if (mode == 1 || mode == 5) {
; #pragma unroll
;                             for (int e = 0; e < 4; ++e) { v0[e] = sigmoidf_(v0[e]); v1[e] = sigmoidf_(v1[e]); } }
;                         if (mode == 6) {
;                             const u32x4 gq = *(const u32x4*)(sG + rl * 256 + cl);
;                             v0[0] *= bflo(gq.x); v0[1] *= bfhi(gq.x); v0[2] *= bflo(gq.y); v0[3] *= bfhi(gq.y); v1[0] *= bflo(gq.z); v1[1] *= bfhi(gq.z); v1[2] *= bflo(gq.w); v1[3] *= bfhi(gq.w);
;                             if (u.br > 0) { const u32x4 mo = *(const u32x4*)(sM + rl * 256 + cl);
;                                 v0[0] += bflo(mo.x); v0[1] += bfhi(mo.x); v0[2] += bflo(mo.y); v0[3] += bfhi(mo.y); v1[0] += bflo(mo.z); v1[1] += bfhi(mo.z); v1[2] += bflo(mo.w); v1[3] += bfhi(mo.w); } }
;                         u32x4 w; w.x = cvtpk(v0[0], v0[1]); w.y = cvtpk(v0[2], v0[3]); w.z = cvtpk(v1[0], v1[1]); w.w = cvtpk(v1[2], v1[3]);
;                         if (mode == 5) *(u32x4*)(sG + rl * 256 + cl) = w;
	v_exp_f32_e32 v141, v141
	v_exp_f32_e32 v142, v142
	v_exp_f32_e32 v143, v143
	v_add_f32_e32 v136, 1.0, v136
	v_add_f32_e32 v137, 1.0, v137
	v_add_f32_e32 v138, 1.0, v138
	v_add_f32_e32 v139, 1.0, v139
	v_add_f32_e32 v140, 1.0, v140
	v_add_f32_e32 v141, 1.0, v141
	v_add_f32_e32 v142, 1.0, v142
	v_add_f32_e32 v143, 1.0, v143
	v_rcp_f32_e32 v136, v136
	v_rcp_f32_e32 v137, v137
	v_rcp_f32_e32 v138, v138
	v_rcp_f32_e32 v139, v139
	v_rcp_f32_e32 v140, v140
	v_rcp_f32_e32 v141, v141
	v_rcp_f32_e32 v142, v142
	v_rcp_f32_e32 v143, v143
	v_cvt_pk_bf16_f32 v210, v136, v137
	v_cvt_pk_bf16_f32 v211, v138, v139
	v_cvt_pk_bf16_f32 v212, v140, v141
	v_cvt_pk_bf16_f32 v213, v142, v143
	global_store_dwordx4 v228, v[210:213], s[90:91] offset:256
	s_add_u32 s90, s90, 0x2000
	s_addc_u32 s91, s91, 0
	v_mul_f32_e32 v136, 0xbfb8aa3b, v60
	v_mul_f32_e32 v137, 0xbfb8aa3b, v61
	v_mul_f32_e32 v138, 0xbfb8aa3b, v62
	v_mul_f32_e32 v139, 0xbfb8aa3b, v63
	v_mul_f32_e32 v140, 0xbfb8aa3b, v56
	v_mul_f32_e32 v141, 0xbfb8aa3b, v57
	v_mul_f32_e32 v142, 0xbfb8aa3b, v58
	v_mul_f32_e32 v143, 0xbfb8aa3b, v59
	v_exp_f32_e32 v136, v136
	v_exp_f32_e32 v137, v137
	v_exp_f32_e32 v138, v138
	v_exp_f32_e32 v139, v139
	v_exp_f32_e32 v140, v140
	v_exp_f32_e32 v141, v141
	v_exp_f32_e32 v142, v142
	v_exp_f32_e32 v143, v143
	v_add_f32_e32 v136, 1.0, v136
	v_add_f32_e32 v137, 1.0, v137
	v_add_f32_e32 v138, 1.0, v138
	v_add_f32_e32 v139, 1.0, v139
	v_add_f32_e32 v140, 1.0, v140
	v_add_f32_e32 v141, 1.0, v141
	v_add_f32_e32 v142, 1.0, v142
	v_add_f32_e32 v143, 1.0, v143
	v_rcp_f32_e32 v136, v136
	v_rcp_f32_e32 v137, v137
	v_rcp_f32_e32 v138, v138
	v_rcp_f32_e32 v139, v139
	v_rcp_f32_e32 v140, v140
	v_rcp_f32_e32 v141, v141
	v_rcp_f32_e32 v142, v142
	v_rcp_f32_e32 v143, v143
	v_cvt_pk_bf16_f32 v246, v136, v137
	v_cvt_pk_bf16_f32 v247, v138, v139
	v_cvt_pk_bf16_f32 v248, v140, v141
	v_cvt_pk_bf16_f32 v249, v142, v143
	global_store_dwordx4 v228, v[246:249], s[90:91]
	v_mul_f32_e32 v136, 0xbfb8aa3b, v28
	v_mul_f32_e32 v137, 0xbfb8aa3b, v29
	v_mul_f32_e32 v138, 0xbfb8aa3b, v30
	v_mul_f32_e32 v139, 0xbfb8aa3b, v31
	v_mul_f32_e32 v140, 0xbfb8aa3b, v24
	v_mul_f32_e32 v141, 0xbfb8aa3b, v25
	v_mul_f32_e32 v142, 0xbfb8aa3b, v26
	v_mul_f32_e32 v143, 0xbfb8aa3b, v27
	v_exp_f32_e32 v136, v136
	v_exp_f32_e32 v137, v137
	v_exp_f32_e32 v138, v138
	v_exp_f32_e32 v139, v139
	v_exp_f32_e32 v140, v140
	v_exp_f32_e32 v141, v141
	v_exp_f32_e32 v142, v142
	v_exp_f32_e32 v143, v143
	v_add_f32_e32 v136, 1.0, v136
	v_add_f32_e32 v137, 1.0, v137
	v_add_f32_e32 v138, 1.0, v138
	v_add_f32_e32 v139, 1.0, v139
	v_add_f32_e32 v140, 1.0, v140
	v_add_f32_e32 v141, 1.0, v141
	v_add_f32_e32 v142, 1.0, v142
	v_add_f32_e32 v143, 1.0, v143
	v_rcp_f32_e32 v136, v136
	v_rcp_f32_e32 v137, v137
	v_rcp_f32_e32 v138, v138
	v_rcp_f32_e32 v139, v139
	v_rcp_f32_e32 v140, v140
	v_rcp_f32_e32 v141, v141
	v_rcp_f32_e32 v142, v142
	v_rcp_f32_e32 v143, v143
	v_cvt_pk_bf16_f32 v210, v136, v137
	v_cvt_pk_bf16_f32 v211, v138, v139
	v_cvt_pk_bf16_f32 v212, v140, v141
	v_cvt_pk_bf16_f32 v213, v142, v143
	global_store_dwordx4 v228, v[210:213], s[90:91] offset:256
	s_add_u32 s90, s90, 0x2000
	s_addc_u32 s91, s91, 0
	v_mul_f32_e32 v136, 0xbfb8aa3b, v52
	v_mul_f32_e32 v137, 0xbfb8aa3b, v53
	v_mul_f32_e32 v138, 0xbfb8aa3b, v54
	v_mul_f32_e32 v139, 0xbfb8aa3b, v55
	v_mul_f32_e32 v140, 0xbfb8aa3b, v48
	v_mul_f32_e32 v141, 0xbfb8aa3b, v49
	v_mul_f32_e32 v142, 0xbfb8aa3b, v50
	v_mul_f32_e32 v143, 0xbfb8aa3b, v51
	v_exp_f32_e32 v136, v136
	v_exp_f32_e32 v137, v137
	v_exp_f32_e32 v138, v138
	v_exp_f32_e32 v139, v139
	v_exp_f32_e32 v140, v140
	v_exp_f32_e32 v141, v141
	v_exp_f32_e32 v142, v142
	v_exp_f32_e32 v143, v143
	v_add_f32_e32 v136, 1.0, v136
	v_add_f32_e32 v137, 1.0, v137
	v_add_f32_e32 v138, 1.0, v138
	v_add_f32_e32 v139, 1.0, v139
	v_add_f32_e32 v140, 1.0, v140
	v_add_f32_e32 v141, 1.0, v141
	v_add_f32_e32 v142, 1.0, v142
	v_add_f32_e32 v143, 1.0, v143
	v_rcp_f32_e32 v136, v136
; __device__ __forceinline__ unsigned cvtpk(float lo, float hi) { f32x2 v = {lo, hi}; bf16x2_t b = __builtin_convertvector(v, bf16x2_t); return __builtin_bit_cast(unsigned, b); }
; __device__ __forceinline__ float bflo(unsigned u) { return __uint_as_float(u << 16); }
; __device__ __forceinline__ float bfhi(unsigned u) { return __uint_as_float(u & 0xffff0000u); }
; __device__ __forceinline__ float sigmoidf_(float x) { return fast_rcp(1.f + __expf(-x)); }
;     __device__ __forceinline__ void operator()(const f32x4 (&acc)[2][2][4][2], const Unit& u, int wr, int wc, int fr, int fq) const {
;     ...
;                         if (mode == 1 || mode == 5) {
; #pragma unroll
;                             for (int e = 0; e < 4; ++e) { v0[e] = sigmoidf_(v0[e]); v1[e] = sigmoidf_(v1[e]); } }
;                         if (mode == 6) {
;                             const u32x4 gq = *(const u32x4*)(sG + rl * 256 + cl);
;                             v0[0] *= bflo(gq.x); v0[1] *= bfhi(gq.x); v0[2] *= bflo(gq.y); v0[3] *= bfhi(gq.y); v1[0] *= bflo(gq.z); v1[1] *= bfhi(gq.z); v1[2] *= bflo(gq.w); v1[3] *= bfhi(gq.w);
;                             if (u.br > 0) { const u32x4 mo = *(const u32x4*)(sM + rl * 256 + cl);
;                                 v0[0] += bflo(mo.x); v0[1] += bfhi(mo.x); v0[2] += bflo(mo.y); v0[3] += bfhi(mo.y); v1[0] += bflo(mo.z); v1[1] += bfhi(mo.z); v1[2] += bflo(mo.w); v1[3] += bfhi(mo.w); } }
;                         u32x4 w; w.x = cvtpk(v0[0], v0[1]); w.y = cvtpk(v0[2], v0[3]); w.z = cvtpk(v1[0], v1[1]); w.w = cvtpk(v1[2], v1[3]);
;                         if (mode == 5) *(u32x4*)(sG + rl * 256 + cl) = w;
	v_rcp_f32_e32 v137, v137
	v_rcp_f32_e32 v138, v138
	v_rcp_f32_e32 v139, v139
	v_rcp_f32_e32 v140, v140
	v_rcp_f32_e32 v141, v141
	v_rcp_f32_e32 v142, v142
	v_rcp_f32_e32 v143, v143
	v_cvt_pk_bf16_f32 v246, v136, v137
	v_cvt_pk_bf16_f32 v247, v138, v139
	v_cvt_pk_bf16_f32 v248, v140, v141
	v_cvt_pk_bf16_f32 v249, v142, v143
	global_store_dwordx4 v228, v[246:249], s[90:91]
	v_mul_f32_e32 v136, 0xbfb8aa3b, v20
	v_mul_f32_e32 v137, 0xbfb8aa3b, v21
	v_mul_f32_e32 v138, 0xbfb8aa3b, v22
	v_mul_f32_e32 v139, 0xbfb8aa3b, v23
	v_mul_f32_e32 v140, 0xbfb8aa3b, v16
	v_mul_f32_e32 v141, 0xbfb8aa3b, v17
	v_mul_f32_e32 v142, 0xbfb8aa3b, v18
	v_mul_f32_e32 v143, 0xbfb8aa3b, v19
	v_exp_f32_e32 v136, v136
	v_exp_f32_e32 v137, v137
	v_exp_f32_e32 v138, v138
	v_exp_f32_e32 v139, v139
	v_exp_f32_e32 v140, v140
	v_exp_f32_e32 v141, v141
	v_exp_f32_e32 v142, v142
	v_exp_f32_e32 v143, v143
	v_add_f32_e32 v136, 1.0, v136
	v_add_f32_e32 v137, 1.0, v137
	v_add_f32_e32 v138, 1.0, v138
	v_add_f32_e32 v139, 1.0, v139
	v_add_f32_e32 v140, 1.0, v140
	v_add_f32_e32 v141, 1.0, v141
	v_add_f32_e32 v142, 1.0, v142
	v_add_f32_e32 v143, 1.0, v143
	v_rcp_f32_e32 v136, v136
	v_rcp_f32_e32 v137, v137
	v_rcp_f32_e32 v138, v138
	v_rcp_f32_e32 v139, v139
	v_rcp_f32_e32 v140, v140
	v_rcp_f32_e32 v141, v141
	v_rcp_f32_e32 v142, v142
	v_rcp_f32_e32 v143, v143
	v_cvt_pk_bf16_f32 v210, v136, v137
	v_cvt_pk_bf16_f32 v211, v138, v139
	v_cvt_pk_bf16_f32 v212, v140, v141
	v_cvt_pk_bf16_f32 v213, v142, v143
	global_store_dwordx4 v228, v[210:213], s[90:91] offset:256
	s_add_u32 s90, s90, 0x2000
	s_addc_u32 s91, s91, 0
	v_mul_f32_e32 v136, 0xbfb8aa3b, v44
	v_mul_f32_e32 v137, 0xbfb8aa3b, v45
	v_mul_f32_e32 v138, 0xbfb8aa3b, v46
	v_mul_f32_e32 v139, 0xbfb8aa3b, v47
	v_mul_f32_e32 v140, 0xbfb8aa3b, v40
	v_mul_f32_e32 v141, 0xbfb8aa3b, v41
	v_mul_f32_e32 v142, 0xbfb8aa3b, v42
	v_mul_f32_e32 v143, 0xbfb8aa3b, v43
	v_exp_f32_e32 v136, v136
	v_exp_f32_e32 v137, v137
	v_exp_f32_e32 v138, v138
	v_exp_f32_e32 v139, v139
	v_exp_f32_e32 v140, v140
	v_exp_f32_e32 v141, v141
	v_exp_f32_e32 v142, v142
	v_exp_f32_e32 v143, v143
	v_add_f32_e32 v136, 1.0, v136
	v_add_f32_e32 v137, 1.0, v137
	v_add_f32_e32 v138, 1.0, v138
	v_add_f32_e32 v139, 1.0, v139
	v_add_f32_e32 v140, 1.0, v140
	v_add_f32_e32 v141, 1.0, v141
	v_add_f32_e32 v142, 1.0, v142
	v_add_f32_e32 v143, 1.0, v143
	v_rcp_f32_e32 v136, v136
	v_rcp_f32_e32 v137, v137
	v_rcp_f32_e32 v138, v138
	v_rcp_f32_e32 v139, v139
	v_rcp_f32_e32 v140, v140
	v_rcp_f32_e32 v141, v141
	v_rcp_f32_e32 v142, v142
	v_rcp_f32_e32 v143, v143
	v_cvt_pk_bf16_f32 v246, v136, v137
	v_cvt_pk_bf16_f32 v247, v138, v139
	v_cvt_pk_bf16_f32 v248, v140, v141
	v_cvt_pk_bf16_f32 v249, v142, v143
	global_store_dwordx4 v228, v[246:249], s[90:91]
	v_mul_f32_e32 v136, 0xbfb8aa3b, v12
	v_mul_f32_e32 v137, 0xbfb8aa3b, v13
	v_mul_f32_e32 v138, 0xbfb8aa3b, v14
	v_mul_f32_e32 v139, 0xbfb8aa3b, v15
	v_mul_f32_e32 v140, 0xbfb8aa3b, v8
	v_mul_f32_e32 v141, 0xbfb8aa3b, v9
	v_mul_f32_e32 v142, 0xbfb8aa3b, v10
	v_mul_f32_e32 v143, 0xbfb8aa3b, v11
	v_exp_f32_e32 v136, v136
	v_exp_f32_e32 v137, v137
	v_exp_f32_e32 v138, v138
	v_exp_f32_e32 v139, v139
	v_exp_f32_e32 v140, v140
	v_exp_f32_e32 v141, v141
	v_exp_f32_e32 v142, v142
	v_exp_f32_e32 v143, v143
	v_add_f32_e32 v136, 1.0, v136
	v_add_f32_e32 v137, 1.0, v137
	v_add_f32_e32 v138, 1.0, v138
	v_add_f32_e32 v139, 1.0, v139
	v_add_f32_e32 v140, 1.0, v140
	v_add_f32_e32 v141, 1.0, v141
	v_add_f32_e32 v142, 1.0, v142
	v_add_f32_e32 v143, 1.0, v143
	v_rcp_f32_e32 v136, v136
	v_rcp_f32_e32 v137, v137
	v_rcp_f32_e32 v138, v138
	v_rcp_f32_e32 v139, v139
	v_rcp_f32_e32 v140, v140
	v_rcp_f32_e32 v141, v141
	v_rcp_f32_e32 v142, v142
	v_rcp_f32_e32 v143, v143
	v_cvt_pk_bf16_f32 v210, v136, v137
	v_cvt_pk_bf16_f32 v211, v138, v139
	v_cvt_pk_bf16_f32 v212, v140, v141
	v_cvt_pk_bf16_f32 v213, v142, v143
	global_store_dwordx4 v228, v[210:213], s[90:91] offset:256
	s_branch .LBB0_422
